# strategy 4: one static priority raise for waves 4-7 in the in-projection K-loop, per-segment setprio flips deleted
# baseline (speedup 1.0000x reference)
.LBB0_171:
	s_or_b64 exec, exec, s[0:1]
	v_mov_b32_e32 v10, v0
	s_cmpk_lt_i32 s64, 0x400
	s_waitcnt lgkmcnt(0)
	s_barrier
	s_cselect_b64 s[0:1], -1, 0
	v_readfirstlane_b32 s98, v0
	s_nop 3
	s_lshr_b32 s98, s98, 6
	s_cmp_ge_u32 s98, 4
	s_cbranch_scc0 .Lprio_done2
	s_setprio 1
.Lprio_done2:
	s_cmpk_gt_i32 s64, 0x3ff
	v_readfirstlane_b32 s8, v10
	s_cbranch_scc1 .LBB0_177
	s_ashr_i32 s2, s64, 31
	s_lshr_b32 s2, s2, 29
	s_add_i32 s6, s64, s2
	s_and_b32 s2, s6, -8
	s_sub_i32 s4, s64, s2
	s_cmp_gt_i32 s4, -1
	s_cbranch_scc0 .LBB0_174
	s_lshl_b32 s5, s4, 7
	s_ashr_i32 s2, s6, 3
	s_cbranch_execz .LBB0_175
	s_branch .LBB0_176

.LBB0_190:
	ds_read_b128 v[148:151], v157
	ds_read_b128 v[152:155], v157 offset:1024
	ds_read_b128 v[162:165], v157 offset:2048
	ds_read_b128 v[166:169], v157 offset:3072
	ds_read_b128 v[170:173], v158
	ds_read_b128 v[174:177], v158 offset:1024
	ds_read_b128 v[178:181], v158 offset:2048
	ds_read_b128 v[182:185], v158 offset:3072
	s_add_u32 s22, s20, 0xfffc0080
	s_addc_u32 s23, s21, -1
	s_cmp_eq_u32 s59, 12
	s_cselect_b32 s29, s5, s23
	s_cselect_b32 s28, s13, s22
	s_cselect_b32 s23, s11, s58
	s_cselect_b32 s22, s56, s57
	v_lshl_add_u64 v[218:219], s[20:21], 0, v[140:141]
	s_add_i32 m0, s19, 0xc000
	ds_read_b128 v[186:189], v159
	ds_read_b128 v[190:193], v159 offset:1024
	ds_read_b128 v[194:197], v159 offset:2048
	ds_read_b128 v[198:201], v159 offset:3072
	ds_read_b128 v[202:205], v159 offset:4096
	ds_read_b128 v[206:209], v159 offset:5120
	ds_read_b128 v[210:213], v159 offset:6144
	ds_read_b128 v[214:217], v159 offset:7168
	global_load_lds_dwordx4 v[218:219], off
	v_lshl_add_u64 v[218:219], s[20:21], 0, v[142:143]
	s_add_i32 m0, s19, 0xe000
	s_nop 0
	global_load_lds_dwordx4 v[218:219], off
	s_waitcnt vmcnt(8)
	s_waitcnt lgkmcnt(0)
	s_barrier
	s_waitcnt lgkmcnt(0)
	v_mfma_f32_16x16x32_bf16 v[126:129], v[148:151], v[186:189], v[126:129]
	v_mfma_f32_16x16x32_bf16 v[122:125], v[162:165], v[186:189], v[122:125]
	v_mfma_f32_16x16x32_bf16 v[110:113], v[148:151], v[194:197], v[110:113]
	v_mfma_f32_16x16x32_bf16 v[106:109], v[162:165], v[194:197], v[106:109]
	v_mfma_f32_16x16x32_bf16 v[94:97], v[148:151], v[202:205], v[94:97]
	v_mfma_f32_16x16x32_bf16 v[90:93], v[162:165], v[202:205], v[90:93]
	v_mfma_f32_16x16x32_bf16 v[78:81], v[148:151], v[210:213], v[78:81]
	v_mfma_f32_16x16x32_bf16 v[74:77], v[162:165], v[210:213], v[74:77]
	v_mfma_f32_16x16x32_bf16 v[126:129], v[152:155], v[190:193], v[126:129]
	v_mfma_f32_16x16x32_bf16 v[122:125], v[166:169], v[190:193], v[122:125]
	v_mfma_f32_16x16x32_bf16 v[110:113], v[152:155], v[198:201], v[110:113]
	v_mfma_f32_16x16x32_bf16 v[106:109], v[166:169], v[198:201], v[106:109]
	v_mfma_f32_16x16x32_bf16 v[94:97], v[152:155], v[206:209], v[94:97]
	v_mfma_f32_16x16x32_bf16 v[90:93], v[166:169], v[206:209], v[90:93]
	v_mfma_f32_16x16x32_bf16 v[78:81], v[152:155], v[214:217], v[78:81]
	v_mfma_f32_16x16x32_bf16 v[74:77], v[166:169], v[214:217], v[74:77]
	v_mfma_f32_16x16x32_bf16 v[118:121], v[170:173], v[186:189], v[118:121]
	v_mfma_f32_16x16x32_bf16 v[114:117], v[178:181], v[186:189], v[114:117]
	v_mfma_f32_16x16x32_bf16 v[102:105], v[170:173], v[194:197], v[102:105]
	v_mfma_f32_16x16x32_bf16 v[98:101], v[178:181], v[194:197], v[98:101]
	v_mfma_f32_16x16x32_bf16 v[86:89], v[170:173], v[202:205], v[86:89]
	v_mfma_f32_16x16x32_bf16 v[82:85], v[178:181], v[202:205], v[82:85]
	v_mfma_f32_16x16x32_bf16 v[70:73], v[170:173], v[210:213], v[70:73]
	v_mfma_f32_16x16x32_bf16 v[66:69], v[178:181], v[210:213], v[66:69]
	v_mfma_f32_16x16x32_bf16 v[118:121], v[174:177], v[190:193], v[118:121]
	v_mfma_f32_16x16x32_bf16 v[114:117], v[182:185], v[190:193], v[114:117]
	v_mfma_f32_16x16x32_bf16 v[102:105], v[174:177], v[198:201], v[102:105]
	v_mfma_f32_16x16x32_bf16 v[98:101], v[182:185], v[198:201], v[98:101]
	v_mfma_f32_16x16x32_bf16 v[86:89], v[174:177], v[206:209], v[86:89]
	v_mfma_f32_16x16x32_bf16 v[82:85], v[182:185], v[206:209], v[82:85]
	v_mfma_f32_16x16x32_bf16 v[70:73], v[174:177], v[214:217], v[70:73]
	v_mfma_f32_16x16x32_bf16 v[66:69], v[182:185], v[214:217], v[66:69]
	s_barrier
	s_add_i32 s60, s43, s33
	v_lshl_add_u64 v[218:219], s[22:23], 0, v[132:133]
	s_mov_b32 m0, s60
	ds_read_b128 v[186:189], v159 offset:16384
	ds_read_b128 v[190:193], v159 offset:17408
	ds_read_b128 v[194:197], v159 offset:18432
	ds_read_b128 v[198:201], v159 offset:19456
	ds_read_b128 v[202:205], v159 offset:20480
	ds_read_b128 v[206:209], v159 offset:21504
	ds_read_b128 v[210:213], v159 offset:22528
	ds_read_b128 v[214:217], v159 offset:23552
	global_load_lds_dwordx4 v[218:219], off
	s_add_i32 m0, s60, 0x2000
	s_add_u32 s60, s22, 0x40000
	v_lshl_add_u64 v[220:221], s[22:23], 0, v[136:137]
	s_addc_u32 s61, s23, 0
	s_add_i32 s62, s44, s33
	global_load_lds_dwordx4 v[220:221], off
	v_lshl_add_u64 v[222:223], s[60:61], 0, v[132:133]
	s_mov_b32 m0, s62
	v_lshl_add_u64 v[224:225], s[28:29], 0, v[134:135]
	global_load_lds_dwordx4 v[222:223], off
	v_lshl_add_u64 v[222:223], s[60:61], 0, v[136:137]
	s_add_i32 m0, s62, 0x2000
	s_nop 0
	global_load_lds_dwordx4 v[222:223], off
	v_lshl_add_u64 v[222:223], s[28:29], 0, v[130:131]
	s_mov_b32 m0, s19
	s_nop 0
	global_load_lds_dwordx4 v[222:223], off
	s_mov_b32 m0, s34
	s_nop 0
	global_load_lds_dwordx4 v[224:225], off
	s_waitcnt vmcnt(8)
	s_waitcnt lgkmcnt(0)
	s_barrier
	s_waitcnt lgkmcnt(0)
	v_mfma_f32_16x16x32_bf16 v[62:65], v[148:151], v[186:189], v[62:65]
	v_mfma_f32_16x16x32_bf16 v[58:61], v[162:165], v[186:189], v[58:61]
	v_mfma_f32_16x16x32_bf16 v[46:49], v[148:151], v[194:197], v[46:49]
	v_mfma_f32_16x16x32_bf16 v[42:45], v[162:165], v[194:197], v[42:45]
	v_mfma_f32_16x16x32_bf16 v[30:33], v[148:151], v[202:205], v[30:33]
	v_mfma_f32_16x16x32_bf16 v[26:29], v[162:165], v[202:205], v[26:29]
	v_mfma_f32_16x16x32_bf16 v[14:17], v[148:151], v[210:213], v[14:17]
	v_mfma_f32_16x16x32_bf16 v[10:13], v[162:165], v[210:213], v[10:13]
	v_mfma_f32_16x16x32_bf16 v[62:65], v[152:155], v[190:193], v[62:65]
	v_mfma_f32_16x16x32_bf16 v[58:61], v[166:169], v[190:193], v[58:61]
	v_mfma_f32_16x16x32_bf16 v[46:49], v[152:155], v[198:201], v[46:49]
	v_mfma_f32_16x16x32_bf16 v[42:45], v[166:169], v[198:201], v[42:45]
	v_mfma_f32_16x16x32_bf16 v[30:33], v[152:155], v[206:209], v[30:33]
	v_mfma_f32_16x16x32_bf16 v[26:29], v[166:169], v[206:209], v[26:29]
	v_mfma_f32_16x16x32_bf16 v[14:17], v[152:155], v[214:217], v[14:17]
	v_mfma_f32_16x16x32_bf16 v[10:13], v[166:169], v[214:217], v[10:13]
	v_mfma_f32_16x16x32_bf16 v[54:57], v[170:173], v[186:189], v[54:57]
	v_mfma_f32_16x16x32_bf16 v[50:53], v[178:181], v[186:189], v[50:53]
	v_mfma_f32_16x16x32_bf16 v[38:41], v[170:173], v[194:197], v[38:41]
	v_mfma_f32_16x16x32_bf16 v[34:37], v[178:181], v[194:197], v[34:37]
	v_mfma_f32_16x16x32_bf16 v[22:25], v[170:173], v[202:205], v[22:25]
	v_mfma_f32_16x16x32_bf16 v[18:21], v[178:181], v[202:205], v[18:21]
	v_mfma_f32_16x16x32_bf16 v[6:9], v[170:173], v[210:213], v[6:9]
	v_mfma_f32_16x16x32_bf16 v[2:5], v[178:181], v[210:213], v[2:5]
	v_mfma_f32_16x16x32_bf16 v[54:57], v[174:177], v[190:193], v[54:57]
	v_mfma_f32_16x16x32_bf16 v[50:53], v[182:185], v[190:193], v[50:53]
	v_mfma_f32_16x16x32_bf16 v[38:41], v[174:177], v[198:201], v[38:41]
	v_mfma_f32_16x16x32_bf16 v[34:37], v[182:185], v[198:201], v[34:37]
	v_mfma_f32_16x16x32_bf16 v[22:25], v[174:177], v[206:209], v[22:25]
	v_mfma_f32_16x16x32_bf16 v[18:21], v[182:185], v[206:209], v[18:21]
	v_mfma_f32_16x16x32_bf16 v[6:9], v[174:177], v[214:217], v[6:9]
	v_mfma_f32_16x16x32_bf16 v[2:5], v[182:185], v[214:217], v[2:5]
	s_barrier
	s_add_i32 s60, 0, 0x18000
	v_add_u32_e32 v138, s60, v156
	s_add_i32 s61, 0, 0x1c000
	ds_read_b128 v[148:151], v138
	ds_read_b128 v[152:155], v138 offset:1024
	ds_read_b128 v[162:165], v138 offset:2048
	ds_read_b128 v[166:169], v138 offset:3072
	v_add_u32_e32 v138, s61, v156
	ds_read_b128 v[170:173], v138
	ds_read_b128 v[174:177], v138 offset:1024
	ds_read_b128 v[178:181], v138 offset:2048
	ds_read_b128 v[182:185], v138 offset:3072
	s_add_u32 s28, s28, 0x40000
	s_addc_u32 s29, s29, 0
	s_mov_b32 m0, s35
	v_lshl_add_u64 v[226:227], s[28:29], 0, v[130:131]
	ds_read_b128 v[186:189], v159 offset:32768
	ds_read_b128 v[190:193], v159 offset:33792
	ds_read_b128 v[194:197], v159 offset:34816
	ds_read_b128 v[198:201], v159 offset:35840
	ds_read_b128 v[202:205], v159 offset:36864
	ds_read_b128 v[206:209], v159 offset:37888
	ds_read_b128 v[210:213], v159 offset:38912
	ds_read_b128 v[214:217], v159 offset:39936
	global_load_lds_dwordx4 v[226:227], off
	v_lshl_add_u64 v[226:227], s[28:29], 0, v[134:135]
	s_mov_b32 m0, s36
	s_nop 0
	global_load_lds_dwordx4 v[226:227], off
	s_waitcnt vmcnt(8)
	s_waitcnt lgkmcnt(0)
	s_barrier
	s_waitcnt lgkmcnt(0)
	v_mfma_f32_16x16x32_bf16 v[126:129], v[148:151], v[186:189], v[126:129]
	v_mfma_f32_16x16x32_bf16 v[122:125], v[162:165], v[186:189], v[122:125]
	v_mfma_f32_16x16x32_bf16 v[110:113], v[148:151], v[194:197], v[110:113]
	v_mfma_f32_16x16x32_bf16 v[106:109], v[162:165], v[194:197], v[106:109]
	v_mfma_f32_16x16x32_bf16 v[94:97], v[148:151], v[202:205], v[94:97]
	v_mfma_f32_16x16x32_bf16 v[90:93], v[162:165], v[202:205], v[90:93]
	v_mfma_f32_16x16x32_bf16 v[78:81], v[148:151], v[210:213], v[78:81]
	v_mfma_f32_16x16x32_bf16 v[74:77], v[162:165], v[210:213], v[74:77]
	v_mfma_f32_16x16x32_bf16 v[126:129], v[152:155], v[190:193], v[126:129]
	v_mfma_f32_16x16x32_bf16 v[122:125], v[166:169], v[190:193], v[122:125]
	v_mfma_f32_16x16x32_bf16 v[110:113], v[152:155], v[198:201], v[110:113]
	v_mfma_f32_16x16x32_bf16 v[106:109], v[166:169], v[198:201], v[106:109]
	v_mfma_f32_16x16x32_bf16 v[94:97], v[152:155], v[206:209], v[94:97]
	v_mfma_f32_16x16x32_bf16 v[90:93], v[166:169], v[206:209], v[90:93]
	v_mfma_f32_16x16x32_bf16 v[78:81], v[152:155], v[214:217], v[78:81]
	v_mfma_f32_16x16x32_bf16 v[74:77], v[166:169], v[214:217], v[74:77]
	v_mfma_f32_16x16x32_bf16 v[118:121], v[170:173], v[186:189], v[118:121]
	v_mfma_f32_16x16x32_bf16 v[114:117], v[178:181], v[186:189], v[114:117]
	v_mfma_f32_16x16x32_bf16 v[102:105], v[170:173], v[194:197], v[102:105]
	v_mfma_f32_16x16x32_bf16 v[98:101], v[178:181], v[194:197], v[98:101]
	v_mfma_f32_16x16x32_bf16 v[86:89], v[170:173], v[202:205], v[86:89]
	v_mfma_f32_16x16x32_bf16 v[82:85], v[178:181], v[202:205], v[82:85]
	v_mfma_f32_16x16x32_bf16 v[70:73], v[170:173], v[210:213], v[70:73]
	v_mfma_f32_16x16x32_bf16 v[66:69], v[178:181], v[210:213], v[66:69]
	v_mfma_f32_16x16x32_bf16 v[118:121], v[174:177], v[190:193], v[118:121]
	v_mfma_f32_16x16x32_bf16 v[114:117], v[182:185], v[190:193], v[114:117]
	v_mfma_f32_16x16x32_bf16 v[102:105], v[174:177], v[198:201], v[102:105]
	v_mfma_f32_16x16x32_bf16 v[98:101], v[182:185], v[198:201], v[98:101]
	v_mfma_f32_16x16x32_bf16 v[86:89], v[174:177], v[206:209], v[86:89]
	v_mfma_f32_16x16x32_bf16 v[82:85], v[182:185], v[206:209], v[82:85]
	v_mfma_f32_16x16x32_bf16 v[70:73], v[174:177], v[214:217], v[70:73]
	v_mfma_f32_16x16x32_bf16 v[66:69], v[182:185], v[214:217], v[66:69]
	s_barrier
	s_add_i32 s28, s60, s33
	v_lshl_add_u64 v[218:219], v[218:219], 0, s[6:7]
	s_mov_b32 m0, s28
	ds_read_b128 v[186:189], v159 offset:49152
	ds_read_b128 v[190:193], v159 offset:50176
	ds_read_b128 v[194:197], v159 offset:51200
	ds_read_b128 v[198:201], v159 offset:52224
	ds_read_b128 v[202:205], v159 offset:53248
	ds_read_b128 v[206:209], v159 offset:54272
	ds_read_b128 v[210:213], v159 offset:55296
	ds_read_b128 v[214:217], v159 offset:56320
	global_load_lds_dwordx4 v[218:219], off
	s_add_i32 m0, s28, 0x2000
	s_add_u32 s22, s22, 0x40080
	v_lshl_add_u64 v[218:219], v[220:221], 0, s[6:7]
	s_addc_u32 s23, s23, 0
	s_add_i32 s28, s61, s33
	global_load_lds_dwordx4 v[218:219], off
	v_lshl_add_u64 v[218:219], s[22:23], 0, v[132:133]
	s_mov_b32 m0, s28
	s_nop 0
	global_load_lds_dwordx4 v[218:219], off
	v_lshl_add_u64 v[218:219], s[22:23], 0, v[136:137]
	s_add_i32 m0, s28, 0x2000
	s_nop 0
	global_load_lds_dwordx4 v[218:219], off
	v_lshl_add_u64 v[218:219], v[222:223], 0, s[6:7]
	s_mov_b32 m0, s39
	s_nop 0
	global_load_lds_dwordx4 v[218:219], off
	v_lshl_add_u64 v[218:219], v[224:225], 0, s[6:7]
	s_mov_b32 m0, s40
	s_nop 0
	global_load_lds_dwordx4 v[218:219], off
	s_waitcnt vmcnt(8)
	s_waitcnt lgkmcnt(0)
	s_barrier
	s_waitcnt lgkmcnt(0)
	v_mfma_f32_16x16x32_bf16 v[62:65], v[148:151], v[186:189], v[62:65]
	v_mfma_f32_16x16x32_bf16 v[58:61], v[162:165], v[186:189], v[58:61]
	v_mfma_f32_16x16x32_bf16 v[46:49], v[148:151], v[194:197], v[46:49]
	v_mfma_f32_16x16x32_bf16 v[42:45], v[162:165], v[194:197], v[42:45]
	v_mfma_f32_16x16x32_bf16 v[30:33], v[148:151], v[202:205], v[30:33]
	v_mfma_f32_16x16x32_bf16 v[26:29], v[162:165], v[202:205], v[26:29]
	v_mfma_f32_16x16x32_bf16 v[14:17], v[148:151], v[210:213], v[14:17]
	v_mfma_f32_16x16x32_bf16 v[10:13], v[162:165], v[210:213], v[10:13]
	v_mfma_f32_16x16x32_bf16 v[62:65], v[152:155], v[190:193], v[62:65]
	v_mfma_f32_16x16x32_bf16 v[58:61], v[166:169], v[190:193], v[58:61]
	v_mfma_f32_16x16x32_bf16 v[46:49], v[152:155], v[198:201], v[46:49]
	v_mfma_f32_16x16x32_bf16 v[42:45], v[166:169], v[198:201], v[42:45]
	v_mfma_f32_16x16x32_bf16 v[30:33], v[152:155], v[206:209], v[30:33]
	v_mfma_f32_16x16x32_bf16 v[26:29], v[166:169], v[206:209], v[26:29]
	v_mfma_f32_16x16x32_bf16 v[14:17], v[152:155], v[214:217], v[14:17]
	v_mfma_f32_16x16x32_bf16 v[10:13], v[166:169], v[214:217], v[10:13]
	v_mfma_f32_16x16x32_bf16 v[54:57], v[170:173], v[186:189], v[54:57]
	v_mfma_f32_16x16x32_bf16 v[50:53], v[178:181], v[186:189], v[50:53]
	v_mfma_f32_16x16x32_bf16 v[38:41], v[170:173], v[194:197], v[38:41]
	v_mfma_f32_16x16x32_bf16 v[34:37], v[178:181], v[194:197], v[34:37]
	v_mfma_f32_16x16x32_bf16 v[22:25], v[170:173], v[202:205], v[22:25]
	v_mfma_f32_16x16x32_bf16 v[18:21], v[178:181], v[202:205], v[18:21]
	v_mfma_f32_16x16x32_bf16 v[6:9], v[170:173], v[210:213], v[6:9]
	v_mfma_f32_16x16x32_bf16 v[2:5], v[178:181], v[210:213], v[2:5]
	v_mfma_f32_16x16x32_bf16 v[54:57], v[174:177], v[190:193], v[54:57]
	v_mfma_f32_16x16x32_bf16 v[50:53], v[182:185], v[190:193], v[50:53]
	v_mfma_f32_16x16x32_bf16 v[38:41], v[174:177], v[198:201], v[38:41]
	v_mfma_f32_16x16x32_bf16 v[34:37], v[182:185], v[198:201], v[34:37]
	v_mfma_f32_16x16x32_bf16 v[22:25], v[174:177], v[206:209], v[22:25]
	v_mfma_f32_16x16x32_bf16 v[18:21], v[182:185], v[206:209], v[18:21]
	v_mfma_f32_16x16x32_bf16 v[6:9], v[174:177], v[214:217], v[6:9]
	v_mfma_f32_16x16x32_bf16 v[2:5], v[182:185], v[214:217], v[2:5]
	s_barrier
	s_add_i32 s59, s59, 2
	s_add_u32 s20, s20, 0x100
	s_addc_u32 s21, s21, 0
	s_add_u32 s57, s57, 0x100
	s_addc_u32 s58, s58, 0
	s_cmp_gt_u32 s59, 13
	s_cbranch_scc0 .LBB0_190
	s_and_b64 vcc, exec, s[8:9]
	s_cbranch_vccz .LBB0_193
	s_barrier

.LBB0_242:
	s_setprio 0
	s_waitcnt vmcnt(0)
	v_readlane_b32 s0, v254, 8
	s_barrier
	v_readlane_b32 s1, v254, 9
	v_readlane_b32 s2, v254, 10
	v_readlane_b32 s3, v254, 11
	v_readlane_b32 s4, v254, 12
	v_readlane_b32 s5, v254, 13
	v_readlane_b32 s6, v254, 14
	v_readlane_b32 s7, v254, 15
	v_readlane_b32 s8, v254, 16
	v_readlane_b32 s9, v254, 17
	v_readlane_b32 s10, v254, 18
	v_readlane_b32 s11, v254, 19
	v_readlane_b32 s12, v254, 20
	v_readlane_b32 s13, v254, 21
	v_readlane_b32 s14, v254, 22
	v_readlane_b32 s15, v254, 23
